# grid barrier: leader keeps wbl2 apart from inv (non-last leaders invalidate before polling, last leader after bumping top generation; no wait before XGEN add), non-leaders invalidate at arrival
# speedup vs baseline: 1.0180x; 1.0059x over previous
.LBB0_150:
	s_andn2_saveexec_b64 s[0:1], s[0:1]
	s_cbranch_execz .LBB0_166
	v_add_co_u32_e32 v6, vcc, 0x3000, v0
	buffer_wbl2 sc1
	s_waitcnt lgkmcnt(0)
	s_waitcnt vmcnt(0)
	v_addc_co_u32_e32 v7, vcc, 0, v1, vcc
	v_mov_b32_e32 v5, 1
	global_atomic_add v5, v[6:7], v5, off offset:1024 sc0
	v_cvt_f32_u32_e32 v6, v4
	v_sub_u32_e32 v8, 0, v4
	s_mov_b64 s[0:1], 0x3500
	s_mov_b64 s[2:3], -1
	v_rcp_iflag_f32_e32 v6, v6
	s_nop 0
	v_mul_f32_e32 v6, 0x4f7ffffe, v6
	v_cvt_u32_f32_e32 v9, v6
	v_lshl_add_u64 v[6:7], v[0:1], 0, s[0:1]
	v_mul_lo_u32 v8, v8, v9
	v_mul_hi_u32 v8, v9, v8
	v_add_u32_e32 v8, v9, v8
	s_waitcnt vmcnt(0)
	v_mul_hi_u32 v8, v5, v8
	v_mul_lo_u32 v10, v8, v4
	v_add_u32_e32 v9, 1, v5
	v_sub_u32_e32 v5, v5, v10
	v_add_u32_e32 v11, 1, v8
	v_cmp_ge_u32_e32 vcc, v5, v4
	v_sub_u32_e32 v10, v5, v4
	s_nop 0
	v_cndmask_b32_e32 v8, v8, v11, vcc
	v_cndmask_b32_e32 v5, v5, v10, vcc
	v_add_u32_e32 v10, 1, v8
	v_cmp_ge_u32_e32 vcc, v5, v4
	s_nop 1
	v_cndmask_b32_e32 v8, v8, v10, vcc
	v_mad_u64_u32 v[4:5], s[0:1], v4, v8, v[4:5]
	v_cmp_ne_u32_e32 vcc, v9, v4
	s_and_saveexec_b64 s[0:1], vcc
	s_cbranch_execz .LBB0_163
	buffer_inv sc1
	global_load_dword v4, v[6:7], off sc1
	s_mov_b64 s[4:5], 0
	s_waitcnt vmcnt(0)
	v_cmp_eq_u32_e32 vcc, v4, v8
	s_and_saveexec_b64 s[2:3], vcc
	s_cbranch_execz .LBB0_162
	s_mov_b64 s[4:5], 0x200
	v_lshl_add_u64 v[4:5], v[0:1], 0, s[4:5]
	s_mov_b32 s16, 1
	s_mov_b64 s[4:5], 0
	s_branch .LBB0_155

.LBB0_163:
	s_or_b64 exec, exec, s[0:1]
	s_and_saveexec_b64 s[0:1], s[2:3]
	s_cbranch_execz .LBB0_165
	v_mov_b32_e32 v0, 1
	global_atomic_add v[6:7], v0, off
	buffer_inv sc1
.LBB0_165:
	s_or_b64 exec, exec, s[0:1]
	v_add_co_u32_e32 v0, vcc, 0x2000, v2
	v_mov_b32_e32 v2, 1
	s_nop 0
	v_addc_co_u32_e32 v1, vcc, 0, v3, vcc
	global_atomic_add v[0:1], v2, off offset:1024
	s_waitcnt vmcnt(0)

.LBB0_212:
	s_or_b64 exec, exec, s[8:9]
	v_cvt_f32_u32_e32 v3, v0
	s_waitcnt vmcnt(0)
	v_readfirstlane_b32 s6, v2
	s_mov_b64 s[10:11], -1
	v_rcp_iflag_f32_e32 v3, v3
	v_add_u32_e32 v1, s6, v1
	v_add_u32_e32 v4, 1, v1
	s_add_u32 s6, s4, 0x3500
	v_mul_f32_e32 v2, 0x4f7ffffe, v3
	v_cvt_u32_f32_e32 v2, v2
	v_sub_u32_e32 v3, 0, v0
	s_addc_u32 s7, s5, 0
	v_mul_lo_u32 v3, v3, v2
	v_mul_hi_u32 v3, v2, v3
	v_add_u32_e32 v2, v2, v3
	v_mul_hi_u32 v2, v1, v2
	v_mul_lo_u32 v3, v2, v0
	v_sub_u32_e32 v1, v1, v3
	v_add_u32_e32 v5, 1, v2
	v_cmp_ge_u32_e32 vcc, v1, v0
	v_sub_u32_e32 v3, v1, v0
	s_nop 0
	v_cndmask_b32_e32 v2, v2, v5, vcc
	v_cndmask_b32_e32 v1, v1, v3, vcc
	v_add_u32_e32 v3, 1, v2
	v_cmp_ge_u32_e32 vcc, v1, v0
	s_nop 1
	v_cndmask_b32_e32 v2, v2, v3, vcc
	v_mul_lo_u32 v1, v0, v2
	v_add_u32_e32 v0, v1, v0
	v_cmp_ne_u32_e32 vcc, v4, v0
	v_mov_b64_e32 v[0:1], s[6:7]
	s_and_saveexec_b64 s[8:9], vcc
	s_cbranch_execz .LBB0_224
	buffer_inv sc1
	global_load_dword v0, v177, s[6:7] sc1
	s_mov_b64 s[14:15], 0
	s_waitcnt vmcnt(0)
	v_cmp_eq_u32_e32 vcc, v0, v2
	s_and_saveexec_b64 s[12:13], vcc
	s_cbranch_execz .LBB0_223
	s_add_u32 s10, s4, 0x200
	s_addc_u32 s11, s5, 0
	s_mov_b32 s22, 1
	s_mov_b64 s[4:5], 0
	s_branch .LBB0_216

.LBB0_224:
	s_or_b64 exec, exec, s[8:9]
	s_and_saveexec_b64 s[4:5], s[10:11]
	s_cbranch_execz .LBB0_226
	v_mov_b32_e32 v2, 1
	global_atomic_add v[0:1], v2, off
	buffer_inv sc1
.LBB0_226:
	s_or_b64 exec, exec, s[4:5]
	s_mov_b64 s[4:5], exec
	v_mbcnt_lo_u32_b32 v0, s4, 0
	v_mbcnt_hi_u32_b32 v0, s5, v0
	v_cmp_eq_u32_e32 vcc, 0, v0
	s_and_saveexec_b64 s[6:7], vcc
	s_cbranch_execz .LBB0_228
	s_bcnt1_i32_b64 s4, s[4:5]
	v_mov_b32_e32 v0, s4
	global_atomic_add v226, v0, s[0:1] offset:1024

.LBB0_270:
	s_or_b64 exec, exec, s[8:9]
	s_waitcnt vmcnt(0)
	v_readfirstlane_b32 s0, v2
	v_cvt_f32_u32_e32 v2, v0
	v_sub_u32_e32 v3, 0, v0
	v_add_u32_e32 v1, s0, v1
	s_add_u32 s0, s4, 0x3500
	v_rcp_iflag_f32_e32 v2, v2
	s_addc_u32 s1, s5, 0
	s_mov_b64 s[10:11], -1
	v_mul_f32_e32 v2, 0x4f7ffffe, v2
	v_cvt_u32_f32_e32 v2, v2
	v_mul_lo_u32 v3, v3, v2
	v_mul_hi_u32 v3, v2, v3
	v_add_u32_e32 v2, v2, v3
	v_mul_hi_u32 v2, v1, v2
	v_mul_lo_u32 v3, v2, v0
	v_sub_u32_e32 v3, v1, v3
	v_cmp_ge_u32_e32 vcc, v3, v0
	v_add_u32_e32 v4, 1, v2
	v_add_u32_e32 v1, 1, v1
	v_cndmask_b32_e32 v2, v2, v4, vcc
	v_sub_u32_e32 v4, v3, v0
	v_cndmask_b32_e32 v3, v3, v4, vcc
	v_cmp_ge_u32_e32 vcc, v3, v0
	v_add_u32_e32 v3, 1, v2
	s_nop 0
	v_cndmask_b32_e32 v2, v2, v3, vcc
	v_mul_lo_u32 v3, v0, v2
	v_add_u32_e32 v0, v3, v0
	v_cmp_ne_u32_e32 vcc, v1, v0
	v_mov_b64_e32 v[0:1], s[0:1]
	s_and_saveexec_b64 s[8:9], vcc
	s_cbranch_execz .LBB0_282
	buffer_inv sc1
	global_load_dword v0, v177, s[0:1] sc1
	s_mov_b64 s[14:15], 0
	s_waitcnt vmcnt(0)
	v_cmp_eq_u32_e32 vcc, v0, v2
	s_and_saveexec_b64 s[12:13], vcc
	s_cbranch_execz .LBB0_281
	s_add_u32 s10, s4, 0x200
	s_addc_u32 s11, s5, 0
	s_mov_b32 s22, 1
	s_mov_b64 s[4:5], 0
	s_branch .LBB0_274

.LBB0_282:
	s_or_b64 exec, exec, s[8:9]
	s_and_saveexec_b64 s[0:1], s[10:11]
	s_cbranch_execz .LBB0_284
	v_mov_b32_e32 v2, 1
	global_atomic_add v[0:1], v2, off
	buffer_inv sc1
.LBB0_284:
	s_or_b64 exec, exec, s[0:1]
	s_mov_b64 s[0:1], exec
	v_mbcnt_lo_u32_b32 v0, s0, 0
	v_mbcnt_hi_u32_b32 v0, s1, v0
	v_cmp_eq_u32_e32 vcc, 0, v0
	s_and_saveexec_b64 s[4:5], vcc
	s_cbranch_execz .LBB0_286
	s_bcnt1_i32_b64 s0, s[0:1]
	v_mov_b32_e32 v0, s0
	global_atomic_add v226, v0, s[6:7] offset:1024

.LBB0_348:
	s_or_b64 exec, exec, s[10:11]
	s_waitcnt vmcnt(0)
	v_readfirstlane_b32 s8, v2
	v_cvt_f32_u32_e32 v2, v0
	v_sub_u32_e32 v3, 0, v0
	v_add_u32_e32 v1, s8, v1
	s_add_u32 s8, s4, 0x3500
	v_rcp_iflag_f32_e32 v2, v2
	s_addc_u32 s9, s5, 0
	s_mov_b64 s[12:13], -1
	v_mul_f32_e32 v2, 0x4f7ffffe, v2
	v_cvt_u32_f32_e32 v2, v2
	v_mul_lo_u32 v3, v3, v2
	v_mul_hi_u32 v3, v2, v3
	v_add_u32_e32 v2, v2, v3
	v_mul_hi_u32 v2, v1, v2
	v_mul_lo_u32 v3, v2, v0
	v_sub_u32_e32 v3, v1, v3
	v_cmp_ge_u32_e32 vcc, v3, v0
	v_add_u32_e32 v4, 1, v2
	v_add_u32_e32 v1, 1, v1
	v_cndmask_b32_e32 v2, v2, v4, vcc
	v_sub_u32_e32 v4, v3, v0
	v_cndmask_b32_e32 v3, v3, v4, vcc
	v_cmp_ge_u32_e32 vcc, v3, v0
	v_add_u32_e32 v3, 1, v2
	s_nop 0
	v_cndmask_b32_e32 v2, v2, v3, vcc
	v_mul_lo_u32 v3, v0, v2
	v_add_u32_e32 v0, v3, v0
	v_cmp_ne_u32_e32 vcc, v1, v0
	v_mov_b64_e32 v[0:1], s[8:9]
	s_and_saveexec_b64 s[10:11], vcc
	s_cbranch_execz .LBB0_360
	buffer_inv sc1
	global_load_dword v0, v177, s[8:9] sc1
	s_mov_b64 s[16:17], 0
	s_waitcnt vmcnt(0)
	v_cmp_eq_u32_e32 vcc, v0, v2
	s_and_saveexec_b64 s[14:15], vcc
	s_cbranch_execz .LBB0_359
	s_add_u32 s12, s4, 0x200
	s_addc_u32 s13, s5, 0
	s_mov_b32 s24, 1
	s_mov_b64 s[4:5], 0
	s_branch .LBB0_352

.LBB0_360:
	s_or_b64 exec, exec, s[10:11]
	s_and_saveexec_b64 s[4:5], s[12:13]
	s_cbranch_execz .LBB0_362
	v_mov_b32_e32 v2, 1
	global_atomic_add v[0:1], v2, off
	buffer_inv sc1
.LBB0_362:
	s_or_b64 exec, exec, s[4:5]
	s_mov_b64 s[4:5], exec
	v_mbcnt_lo_u32_b32 v0, s4, 0
	v_mbcnt_hi_u32_b32 v0, s5, v0
	v_cmp_eq_u32_e32 vcc, 0, v0
	s_and_saveexec_b64 s[8:9], vcc
	s_cbranch_execz .LBB0_364
	s_bcnt1_i32_b64 s4, s[4:5]
	v_mov_b32_e32 v0, s4
	global_atomic_add v226, v0, s[6:7] offset:1024

.LBB0_1014:
	s_or_b64 exec, exec, s[10:11]
	v_cvt_f32_u32_e32 v3, v0
	s_waitcnt vmcnt(0)
	v_readfirstlane_b32 s8, v2
	s_mov_b64 s[12:13], -1
	v_rcp_iflag_f32_e32 v3, v3
	v_add_u32_e32 v1, s8, v1
	v_add_u32_e32 v4, 1, v1
	s_add_u32 s8, s4, 0x3500
	v_mul_f32_e32 v2, 0x4f7ffffe, v3
	v_cvt_u32_f32_e32 v2, v2
	v_sub_u32_e32 v3, 0, v0
	s_addc_u32 s9, s5, 0
	v_mul_lo_u32 v3, v3, v2
	v_mul_hi_u32 v3, v2, v3
	v_add_u32_e32 v2, v2, v3
	v_mul_hi_u32 v2, v1, v2
	v_mul_lo_u32 v3, v2, v0
	v_sub_u32_e32 v1, v1, v3
	v_add_u32_e32 v5, 1, v2
	v_cmp_ge_u32_e32 vcc, v1, v0
	v_sub_u32_e32 v3, v1, v0
	s_nop 0
	v_cndmask_b32_e32 v2, v2, v5, vcc
	v_cndmask_b32_e32 v1, v1, v3, vcc
	v_add_u32_e32 v3, 1, v2
	v_cmp_ge_u32_e32 vcc, v1, v0
	s_nop 1
	v_cndmask_b32_e32 v2, v2, v3, vcc
	v_mul_lo_u32 v1, v0, v2
	v_add_u32_e32 v0, v1, v0
	v_cmp_ne_u32_e32 vcc, v4, v0
	v_mov_b64_e32 v[0:1], s[8:9]
	s_and_saveexec_b64 s[10:11], vcc
	s_cbranch_execz .LBB0_1026
	buffer_inv sc1
	global_load_dword v0, v177, s[8:9] sc1
	s_mov_b64 s[16:17], 0
	s_waitcnt vmcnt(0)
	v_cmp_eq_u32_e32 vcc, v0, v2
	s_and_saveexec_b64 s[14:15], vcc
	s_cbranch_execz .LBB0_1025
	s_add_u32 s12, s4, 0x200
	s_addc_u32 s13, s5, 0
	s_mov_b32 s24, 1
	s_mov_b64 s[4:5], 0
	s_branch .LBB0_1018

.LBB0_1028:
	s_or_b64 exec, exec, s[4:5]
	s_mov_b64 s[4:5], exec
	v_mbcnt_lo_u32_b32 v0, s4, 0
	v_mbcnt_hi_u32_b32 v0, s5, v0
	v_cmp_eq_u32_e32 vcc, 0, v0
	s_and_saveexec_b64 s[8:9], vcc
	s_cbranch_execz .LBB0_1030
	s_bcnt1_i32_b64 s4, s[4:5]
	v_mov_b32_e32 v0, s4
	global_atomic_add v226, v0, s[0:1] offset:1024

.LBB0_1451:
	s_or_b64 exec, exec, s[10:11]
	s_waitcnt vmcnt(0)
	v_readfirstlane_b32 s0, v2
	v_cvt_f32_u32_e32 v2, v0
	v_sub_u32_e32 v3, 0, v0
	v_add_u32_e32 v1, s0, v1
	s_add_u32 s2, s6, 0x3500
	v_rcp_iflag_f32_e32 v2, v2
	s_addc_u32 s3, s7, 0
	s_mov_b64 s[12:13], -1
	v_mul_f32_e32 v2, 0x4f7ffffe, v2
	v_cvt_u32_f32_e32 v2, v2
	v_mul_lo_u32 v3, v3, v2
	v_mul_hi_u32 v3, v2, v3
	v_add_u32_e32 v2, v2, v3
	v_mul_hi_u32 v2, v1, v2
	v_mul_lo_u32 v3, v2, v0
	v_sub_u32_e32 v3, v1, v3
	v_cmp_ge_u32_e32 vcc, v3, v0
	v_add_u32_e32 v4, 1, v2
	v_add_u32_e32 v1, 1, v1
	v_cndmask_b32_e32 v2, v2, v4, vcc
	v_sub_u32_e32 v4, v3, v0
	v_cndmask_b32_e32 v3, v3, v4, vcc
	v_cmp_ge_u32_e32 vcc, v3, v0
	v_add_u32_e32 v3, 1, v2
	s_nop 0
	v_cndmask_b32_e32 v2, v2, v3, vcc
	v_mul_lo_u32 v3, v0, v2
	v_add_u32_e32 v0, v3, v0
	v_cmp_ne_u32_e32 vcc, v1, v0
	v_mov_b64_e32 v[0:1], s[2:3]
	s_and_saveexec_b64 s[10:11], vcc
	s_cbranch_execz .LBB0_1463
	buffer_inv sc1
	global_load_dword v0, v177, s[2:3] sc1
	s_mov_b64 s[16:17], 0
	s_waitcnt vmcnt(0)
	v_cmp_eq_u32_e32 vcc, v0, v2
	s_and_saveexec_b64 s[14:15], vcc
	s_cbranch_execz .LBB0_1462
	s_add_u32 s12, s6, 0x200
	s_addc_u32 s13, s7, 0
	s_mov_b32 s24, 1
	s_mov_b64 s[6:7], 0
	s_branch .LBB0_1455

.LBB0_1463:
	s_or_b64 exec, exec, s[10:11]
	s_and_saveexec_b64 s[2:3], s[12:13]
	s_cbranch_execz .LBB0_1465
	v_mov_b32_e32 v2, 1
	global_atomic_add v[0:1], v2, off
	buffer_inv sc1
.LBB0_1465:
	s_or_b64 exec, exec, s[2:3]
	s_mov_b64 s[2:3], exec
	v_mbcnt_lo_u32_b32 v0, s2, 0
	v_mbcnt_hi_u32_b32 v0, s3, v0
	v_cmp_eq_u32_e32 vcc, 0, v0
	s_and_saveexec_b64 s[6:7], vcc
	s_cbranch_execz .LBB0_1467
	s_bcnt1_i32_b64 s0, s[2:3]
	v_mov_b32_e32 v0, s0
	global_atomic_add v226, v0, s[8:9] offset:1024

.LBB0_1673:
	s_or_b64 exec, exec, s[0:1]
	s_mov_b64 s[0:1], exec
	v_mbcnt_lo_u32_b32 v0, s0, 0
	v_mbcnt_hi_u32_b32 v0, s1, v0
	v_cmp_eq_u32_e32 vcc, 0, v0
	s_and_saveexec_b64 s[4:5], vcc
	s_cbranch_execnz .LBB0_1674
	s_getpc_b64 s[98:99]
